# k29: scan state-chain waves 0 and 2: step counters + exit test moved in front of the step barrier; hipcc's multi-branch active-step test replaced by one unsigned range compare
# speedup vs baseline: 1.0018x; 1.0018x over previous
.LBB0_816:
	s_add_u32 s0, s0, 0x1000
	s_addc_u32 s1, s1, 0
	s_add_u32 s12, s12, 0x8000
	s_addc_u32 s13, s13, 0
	s_add_i32 s33, s33, 1
	s_add_u32 s68, s68, s34
	s_addc_u32 s69, s69, s35
	s_cmp_eq_u32 s12, 0x1020000
	s_waitcnt lgkmcnt(0)
	s_barrier
	s_cbranch_scc1 .LBB0_830
.LBB0_817:
	s_add_i32 s38, s33, -4
	s_add_i32 s4, s33, -7
	s_cmpk_lt_u32 s4, 0x200
	s_cbranch_scc1 .LBB0_824
	s_cmpk_gt_u32 s38, 0x1fb
	s_mov_b64 s[4:5], -1
	s_cbranch_scc1 .LBB0_825

.LBB0_833:
	s_addk_i32 s6, 0x1000
	s_add_i32 s7, s7, 1
	s_cmp_eq_u32 s6, 0x201000
	s_waitcnt lgkmcnt(0)
	s_barrier
	s_cbranch_scc1 .LBB0_840
.LBB0_834:
	s_cmpk_gt_u32 s7, 0x1ff
	s_cbranch_scc1 .LBB0_833
	s_and_b32 s0, s7, 3
	s_mulk_i32 s0, 0x5f00
	s_add_i32 s0, s0, 0
	v_lshlrev_b32_e32 v0, 1, v78
	v_lshlrev_b32_e32 v4, 1, v77
	v_add3_u32 v14, s0, v0, v4
	ds_read_b128 v[0:3], v14 offset:19968
	ds_read_b128 v[64:67], v14 offset:14336
	v_add3_u32 v9, s0, v76, v4
	v_cvt_pk_bf16_f32 v4, v16, v17
	s_waitcnt lgkmcnt(0)
	v_mfma_f32_32x32x16_bf16 v[48:63], v[0:3], v[64:67], 0
	ds_read_b128 v[0:3], v9
	ds_read_b128 v[10:13], v9 offset:64
	v_cvt_pk_bf16_f32 v5, v18, v19
	v_cvt_pk_bf16_f32 v6, v20, v21
	v_cvt_pk_bf16_f32 v7, v22, v23
	v_add_u32_e32 v69, v14, v80
	ds_read_b128 v[82:85], v9 offset:96
	s_waitcnt lgkmcnt(2)
	v_mfma_f32_32x32x16_bf16 v[48:63], v[0:3], v[4:7], v[48:63]
	ds_read_b128 v[0:3], v9 offset:32
	v_cvt_pk_bf16_f32 v4, v24, v25
	v_cvt_pk_bf16_f32 v5, v26, v27
	v_cvt_pk_bf16_f32 v6, v28, v29
	v_cvt_pk_bf16_f32 v7, v30, v31
	ds_read_b128 v[70:73], v69 offset:17440
	v_lshl_add_u32 v74, v79, 2, s0
	s_waitcnt lgkmcnt(1)
	v_mfma_f32_32x32x16_bf16 v[48:63], v[0:3], v[4:7], v[48:63]
	v_cvt_pk_bf16_f32 v0, v32, v33
	v_cvt_pk_bf16_f32 v1, v34, v35
	v_cvt_pk_bf16_f32 v2, v36, v37
	v_cvt_pk_bf16_f32 v3, v38, v39
	v_cvt_pk_bf16_f32 v4, v40, v41
	v_cvt_pk_bf16_f32 v5, v42, v43
	v_cvt_pk_bf16_f32 v6, v44, v45
	v_mfma_f32_32x32x16_bf16 v[48:63], v[10:13], v[0:3], v[48:63]
	v_cvt_pk_bf16_f32 v7, v46, v47
	ds_read_b128 v[86:89], v14 offset:21504
	ds_read_b128 v[90:93], v74 offset:24064
	v_mov_b32_e32 v14, v8
	v_mov_b32_e32 v15, v8
	v_mov_b32_e32 v9, v8
	v_mov_b32_e32 v10, v8
	v_mov_b32_e32 v11, v8
	v_mfma_f32_32x32x16_bf16 v[48:63], v[82:85], v[4:7], v[48:63]
	ds_read_b128 v[82:85], v69 offset:17408
	v_mov_b32_e32 v12, v8
	v_mov_b32_e32 v13, v8
	s_and_b32 s1, s6, 0x1000
	s_waitcnt lgkmcnt(1)
	v_pk_mul_f32 v[18:19], v[18:19], v[92:93]
	v_pk_mul_f32 v[16:17], v[16:17], v[90:91]
	s_nop 4
	v_cvt_pk_bf16_f32 v48, v48, v49
	v_cvt_pk_bf16_f32 v49, v50, v51
	v_cvt_pk_bf16_f32 v50, v52, v53
	v_cvt_pk_bf16_f32 v51, v54, v55
	v_mov_b32_e32 v0, v56
	v_mov_b32_e32 v1, v57
	v_mov_b32_e32 v2, v58
	v_mov_b32_e32 v3, v59
	v_mov_b32_e32 v4, v60
	v_mov_b32_e32 v5, v61
	v_mov_b32_e32 v6, v62
	v_mov_b32_e32 v7, v63
	v_mfma_f32_32x32x16_bf16 v[48:63], v[86:89], v[48:51], 0
	s_nop 11
	v_cvt_pk_bf16_f32 v86, v48, v49
	v_cvt_pk_bf16_f32 v87, v50, v51
	v_cvt_pk_bf16_f32 v88, v52, v53
	v_cvt_pk_bf16_f32 v89, v54, v55
	v_mov_b64_e32 v[62:63], v[14:15]
	v_mov_b64_e32 v[60:61], v[12:13]
	v_mov_b64_e32 v[58:59], v[10:11]
	v_mov_b64_e32 v[56:57], v[8:9]
	v_mov_b64_e32 v[54:55], v[6:7]
	v_mov_b64_e32 v[52:53], v[4:5]
	v_mov_b64_e32 v[50:51], v[2:3]
	v_mov_b64_e32 v[48:49], v[0:1]
	ds_read_b128 v[0:3], v74 offset:24112
	v_add_u32_e32 v9, s1, v68
	s_waitcnt lgkmcnt(1)
	v_mfma_f32_32x32x16_bf16 v[48:63], v[82:85], v[86:89], v[48:63]
	v_add_u32_e32 v14, 0x400, v9
	ds_read_b128 v[4:7], v74 offset:24080
	ds_read_b128 v[10:13], v74 offset:24096
	ds_read_b128 v[82:85], v74 offset:24176
	s_waitcnt lgkmcnt(3)
	v_pk_mul_f32 v[28:29], v[28:29], v[0:1]
	v_pk_mul_f32 v[30:31], v[30:31], v[2:3]
	s_waitcnt lgkmcnt(2)
	v_pk_mul_f32 v[20:21], v[20:21], v[4:5]
	s_waitcnt lgkmcnt(1)
	v_pk_mul_f32 v[24:25], v[24:25], v[10:11]
	v_pk_mul_f32 v[26:27], v[26:27], v[12:13]
	v_mfma_f32_32x32x16_bf16 v[48:63], v[70:73], v[64:67], v[48:63]
	s_nop 11
	ds_write2_b32 v9, v48, v49 offset1:32
	ds_write2_b32 v9, v50, v51 offset0:64 offset1:96
	ds_write2_b32 v14, v52, v53 offset1:32
	ds_write2_b32 v14, v54, v55 offset0:64 offset1:96
	ds_read_b128 v[48:51], v69 offset:9216
	ds_read_b128 v[0:3], v69 offset:9248
	v_pk_mul_f32 v[22:23], v[22:23], v[6:7]
	s_waitcnt lgkmcnt(6)
	v_pk_mul_f32 v[44:45], v[44:45], v[82:83]
	v_pk_mul_f32 v[46:47], v[46:47], v[84:85]
	s_waitcnt lgkmcnt(1)
	v_mfma_f32_32x32x16_bf16 v[16:31], v[48:51], v[86:89], v[16:31]
	ds_read_b128 v[4:7], v74 offset:24160
	ds_read_b128 v[10:13], v74 offset:24128
	ds_read_b128 v[48:51], v74 offset:24144
	ds_read_b128 v[52:55], v69 offset:11776
	s_waitcnt lgkmcnt(3)
	v_pk_mul_f32 v[40:41], v[40:41], v[4:5]
	v_pk_mul_f32 v[42:43], v[42:43], v[6:7]
	s_waitcnt lgkmcnt(1)
	v_pk_mul_f32 v[36:37], v[36:37], v[48:49]
	v_pk_mul_f32 v[38:39], v[38:39], v[50:51]
	v_mfma_f32_32x32x16_bf16 v[16:31], v[0:3], v[64:67], v[16:31]
	v_mul_f32_e64 v34, v34, v12
	v_mul_f32_e64 v35, v35, v13
	v_mul_f32_e64 v32, v32, v10
	v_mul_f32_e64 v33, v33, v11
	ds_read_b128 v[0:3], v69 offset:11808
	s_waitcnt lgkmcnt(1)
	v_mfma_f32_32x32x16_bf16 v[32:47], v[52:55], v[86:89], v[32:47]
	s_waitcnt lgkmcnt(0)
	v_mfma_f32_32x32x16_bf16 v[32:47], v[0:3], v[64:67], v[32:47]
	s_branch .LBB0_833
